# hot loop heads (GEMM K-loops, NSA step loops, conversion/row loops) pinned to 64-byte boundaries with .p2align
# speedup vs baseline: 1.0114x; 1.0114x over previous
; #define LAS __attribute__((address_space(3)))
; template <bool FP8, class Epi, class Sched, class ARow, class BBase>
; __device__ __forceinline__ void gemm_phase(LAS unsigned char* lds, const void* Abase, const ARow& AR, const BBase& BB, const Sched& S, const Epi& E, int tid) {
;     ...
;             *(LAS u32x4*)(lds + NA_OFF + tid * 16) = (u32x4){nA[0][0], nA[0][1], nA[1][0], nA[1][1]};
;         }
;         if constexpr (Epi::PREFETCH) E.prefetch(lds + (ui & 1) * SB_SIZE, cur, tid);
;         for (int t = 0; t < nt; t += 2) {
;     ...
;         for (int a = 0; a < 2; ++a)
; #pragma unroll
;             for (int b = 0; b < 2; ++b)
; #pragma unroll
;                 for (int m = 0; m < 4; ++m)
; #pragma unroll
;                     for (int n = 0; n < 2; ++n) acc[a][b][m][n] = (f32x4){0.f, 0.f, 0.f, 0.f};
.LBB0_550:
	s_waitcnt vmcnt(0)
	v_add_u32_e32 v10, 0, v1
	v_add_u32_e32 v198, 0x20400, v10
	ds_write_b128 v198, v[6:9]
	s_add_u32 s4, s14, 0x100
	v_mov_b32_e32 v6, 0
	s_addc_u32 s5, s15, 0
	s_mov_b32 s31, -2
	s_mov_b64 s[14:15], 0
	v_mov_b32_e32 v7, v6
	v_mov_b32_e32 v8, v6
	v_mov_b32_e32 v9, v6
	v_mov_b32_e32 v10, v6
	v_mov_b32_e32 v11, v6
	v_mov_b32_e32 v12, v6
	v_mov_b32_e32 v13, v6
	v_mov_b32_e32 v22, v6
	v_mov_b32_e32 v23, v6
	v_mov_b32_e32 v24, v6
	v_mov_b32_e32 v25, v6
	v_mov_b32_e32 v26, v6
	v_mov_b32_e32 v27, v6
	v_mov_b32_e32 v28, v6
	v_mov_b32_e32 v29, v6
	v_mov_b32_e32 v38, v6
	v_mov_b32_e32 v39, v6
	v_mov_b32_e32 v40, v6
	v_mov_b32_e32 v41, v6
	v_mov_b32_e32 v42, v6
	v_mov_b32_e32 v43, v6
	v_mov_b32_e32 v44, v6
	v_mov_b32_e32 v45, v6
	v_mov_b32_e32 v54, v6
	v_mov_b32_e32 v55, v6
	v_mov_b32_e32 v56, v6
	v_mov_b32_e32 v57, v6
	v_mov_b32_e32 v58, v6
	v_mov_b32_e32 v59, v6
	v_mov_b32_e32 v60, v6
	v_mov_b32_e32 v61, v6
	v_mov_b32_e32 v14, v6
	v_mov_b32_e32 v15, v6
	v_mov_b32_e32 v16, v6
	v_mov_b32_e32 v17, v6
	v_mov_b32_e32 v18, v6
	v_mov_b32_e32 v19, v6
	v_mov_b32_e32 v20, v6
	v_mov_b32_e32 v21, v6
	v_mov_b32_e32 v30, v6
	v_mov_b32_e32 v31, v6
	v_mov_b32_e32 v32, v6
	v_mov_b32_e32 v33, v6
	v_mov_b32_e32 v34, v6
	v_mov_b32_e32 v35, v6
	v_mov_b32_e32 v36, v6
	v_mov_b32_e32 v37, v6
	v_mov_b32_e32 v46, v6
	v_mov_b32_e32 v47, v6
	v_mov_b32_e32 v48, v6
	v_mov_b32_e32 v49, v6
	v_mov_b32_e32 v50, v6
	v_mov_b32_e32 v51, v6
	v_mov_b32_e32 v52, v6
	v_mov_b32_e32 v53, v6
	v_mov_b32_e32 v62, v6
	v_mov_b32_e32 v63, v6
	v_mov_b32_e32 v64, v6
	v_mov_b32_e32 v65, v6
	v_mov_b32_e32 v66, v6
	v_mov_b32_e32 v67, v6
	v_mov_b32_e32 v68, v6
	v_mov_b32_e32 v69, v6
	v_mov_b32_e32 v70, v6
	v_mov_b32_e32 v71, v6
	v_mov_b32_e32 v72, v6
	v_mov_b32_e32 v73, v6
	v_mov_b32_e32 v74, v6
	v_mov_b32_e32 v75, v6
	v_mov_b32_e32 v76, v6
	v_mov_b32_e32 v77, v6
	v_mov_b32_e32 v86, v6
	v_mov_b32_e32 v87, v6
	v_mov_b32_e32 v88, v6
	v_mov_b32_e32 v89, v6
	v_mov_b32_e32 v90, v6
	v_mov_b32_e32 v91, v6
	v_mov_b32_e32 v92, v6
	v_mov_b32_e32 v93, v6
	v_mov_b32_e32 v102, v6
	v_mov_b32_e32 v103, v6
	v_mov_b32_e32 v104, v6
	v_mov_b32_e32 v105, v6
	v_mov_b32_e32 v106, v6
	v_mov_b32_e32 v107, v6
	v_mov_b32_e32 v108, v6
	v_mov_b32_e32 v109, v6
	v_mov_b32_e32 v118, v6
	v_mov_b32_e32 v119, v6
	v_mov_b32_e32 v120, v6
	v_mov_b32_e32 v121, v6
	v_mov_b32_e32 v122, v6
	v_mov_b32_e32 v123, v6
	v_mov_b32_e32 v124, v6
	v_mov_b32_e32 v125, v6
	v_mov_b32_e32 v78, v6
	v_mov_b32_e32 v79, v6
	v_mov_b32_e32 v80, v6
	v_mov_b32_e32 v81, v6
	v_mov_b32_e32 v82, v6
	v_mov_b32_e32 v83, v6
	v_mov_b32_e32 v84, v6
	v_mov_b32_e32 v85, v6
	v_mov_b32_e32 v94, v6
	v_mov_b32_e32 v95, v6
	v_mov_b32_e32 v96, v6
	v_mov_b32_e32 v97, v6
	v_mov_b32_e32 v98, v6
	v_mov_b32_e32 v99, v6
	v_mov_b32_e32 v100, v6
	v_mov_b32_e32 v101, v6
	v_mov_b32_e32 v110, v6
	v_mov_b32_e32 v111, v6
	v_mov_b32_e32 v112, v6
	v_mov_b32_e32 v113, v6
	v_mov_b32_e32 v114, v6
	v_mov_b32_e32 v115, v6
	v_mov_b32_e32 v116, v6
	v_mov_b32_e32 v117, v6
	v_mov_b32_e32 v126, v6
	v_mov_b32_e32 v127, v6
	v_mov_b32_e32 v128, v6
	v_mov_b32_e32 v129, v6
	v_mov_b32_e32 v130, v6
	v_mov_b32_e32 v131, v6
	v_mov_b32_e32 v132, v6
	v_mov_b32_e32 v133, v6
	.p2align	6

; #define LAS __attribute__((address_space(3)))
;     ...
;     const int sr = tid >> 2, sc = (tid & 3) * 8;
;     const bf16* srcA0 = A + (size_t)arow(sr) * D + sc;
;     const bf16* srcA1 = A + (size_t)arow(sr + 128) * D + sc;
;     const bf16* srcB = Bt + (size_t)sr * ldb + sc;
;     LAS unsigned char* lds = F.lds;
;     f32x4 acc[4][4];
; #pragma unroll
;     for (int m = 0; m < 4; ++m)
; #pragma unroll
;         for (int n = 0; n < 4; ++n) acc[m][n] = (f32x4){0.f, 0.f, 0.f, 0.f};
;     ...
;     const int aoff = (cx.wr * 64 + cx.fr) * 64 + cx.fq * 16, boff = (cx.wc * 64 + cx.fr) * 64 + cx.fq * 16;
;     __syncthreads();
;     STAGE(0, 0); if (nk > 1) STAGE(1, 1); if (nk > 2) STAGE(2, 2);
;     for (int t = 0; t < nk; ++t) {
; __device__ __forceinline__ void phase_prep(const Frame& F, int l) {
;     ...
;             for (int u = F.bid; u < 16; u += F.G) { const int which = u >> 3, p0 = (u & 7) * 2, lw = l * 2 + which;
;                 RowCmp R{p0}; EpiCmp E{F.lds, (unsigned char*)F.ws, (const float*)(F.ws + WS_CB1) + lw * 128, (const bf16*)(F.ws + WS_CW2T) + (size_t)lw * 64 * 128, which, p0, F.wave};
;                 gemm_unit(F, (const bf16*)(F.ws + (which ? WS_NVC : WS_NKC)), R, (const bf16*)(F.ws + WS_CW1T) + (size_t)lw * 128 * 2048, E, 64, 2048); }
.LBB0_1042:
	s_lshl_b32 s0, s37, 7
	s_and_b32 s3, s0, 0x700
	s_ashr_i32 s7, s40, 3
	s_lshl_b32 s0, s40, 1
	s_and_b32 s6, s0, 14
	s_add_i32 s0, s7, s28
	s_ashr_i32 s1, s0, 31
	s_cmp_gt_u32 s40, 7
	s_cselect_b64 s[14:15], -1, 0
	s_cmp_lt_u32 s40, 8
	s_mov_b32 s4, 0x6d800000
	s_cselect_b32 s34, s4, 0x6dc00000
	v_lshl_add_u32 v4, s6, 7, v70
	s_add_u32 s4, s78, s34
	v_ashrrev_i32_e32 v5, 31, v4
	s_addc_u32 s5, s79, 0
	v_lshlrev_b64 v[4:5], 11, v[4:5]
	v_lshl_add_u64 v[4:5], s[4:5], 0, v[4:5]
	v_mov_b32_e32 v99, v199
	v_lshl_add_u64 v[4:5], v[4:5], 0, v[98:99]
	s_mov_b64 s[4:5], 0x40000
	v_lshl_add_u64 v[6:7], v[4:5], 0, s[4:5]
	v_readfirstlane_b32 s4, v85
	v_add_u32_e32 v3, 0x2000, v85
	s_mov_b32 m0, s4
	v_readfirstlane_b32 s4, v3
	v_add_u32_e32 v3, 0x4000, v85
	s_lshl_b64 s[26:27], s[0:1], 19
	s_barrier
	global_load_lds_dwordx4 v[4:5], off
	s_mov_b32 m0, s4
	v_readfirstlane_b32 s4, v3
	v_add_u32_e32 v3, 0x6000, v85
	v_lshl_add_u64 v[8:9], v[72:73], 0, s[26:27]
	global_load_lds_dwordx4 v[6:7], off
	s_mov_b32 m0, s4
	v_readfirstlane_b32 s4, v3
	global_load_lds_dwordx4 v[8:9], off
	v_lshl_add_u64 v[6:7], v[4:5], 0, 64
	s_mov_b32 m0, s4
	s_mov_b64 s[4:5], 0x40040
	v_add_u32_e32 v3, 0x8000, v85
	global_load_lds_dwordx4 v[6:7], off
	v_lshl_add_u64 v[6:7], v[4:5], 0, s[4:5]
	v_readfirstlane_b32 s4, v3
	v_add_u32_e32 v3, 0xa000, v85
	s_mov_b32 m0, s4
	v_readfirstlane_b32 s4, v3
	v_add_u32_e32 v3, 0xc000, v85
	global_load_lds_dwordx4 v[6:7], off
	v_lshl_add_u64 v[6:7], v[8:9], 0, 64
	s_mov_b32 m0, s4
	v_readfirstlane_b32 s4, v3
	global_load_lds_dwordx4 v[6:7], off
	s_mov_b32 m0, s4
	s_mov_b64 s[4:5], 0x40080
	v_add_u32_e32 v3, 0xe000, v85
	v_lshl_add_u64 v[6:7], v[4:5], 0, s[18:19]
	v_lshl_add_u64 v[4:5], v[4:5], 0, s[4:5]
	v_readfirstlane_b32 s4, v3
	global_load_lds_dwordx4 v[6:7], off
	s_mov_b32 m0, s4
	s_add_i32 s4, 0, 0x10000
	v_add_u32_e32 v3, s4, v83
	global_load_lds_dwordx4 v[4:5], off
	v_readfirstlane_b32 s4, v3
	v_lshl_add_u64 v[4:5], v[8:9], 0, s[18:19]
	s_mov_b32 m0, s4
	v_add_u32_e32 v2, s3, v109
	global_load_lds_dwordx4 v[4:5], off
	v_ashrrev_i32_e32 v3, 31, v2
	v_add_u32_e32 v4, s3, v70
	v_lshlrev_b64 v[2:3], 11, v[2:3]
	v_ashrrev_i32_e32 v5, 31, v4
	v_readlane_b32 s4, v249, 41
	v_lshlrev_b64 v[4:5], 11, v[4:5]
	s_add_i32 s4, s4, s7
	v_lshl_add_u64 v[2:3], s[34:35], 0, v[2:3]
	s_ashr_i32 s5, s4, 31
	v_lshl_add_u64 v[68:69], v[96:97], 0, v[2:3]
	v_lshl_add_u64 v[2:3], s[34:35], 0, v[4:5]
	s_lshl_b64 s[4:5], s[4:5], 19
	v_lshl_add_u64 v[106:107], v[96:97], 0, v[2:3]
	v_mov_b32_e32 v2, 0
	s_mov_b32 s3, 3
	v_lshl_add_u64 v[66:67], v[94:95], 0, s[4:5]
	s_mov_b64 s[26:27], 0
	v_mov_b32_e32 v3, v2
	v_mov_b32_e32 v4, v2
	v_mov_b32_e32 v5, v2
	v_mov_b32_e32 v6, v2
	v_mov_b32_e32 v7, v2
	v_mov_b32_e32 v8, v2
	v_mov_b32_e32 v9, v2
	v_mov_b32_e32 v10, v2
	v_mov_b32_e32 v11, v2
	v_mov_b32_e32 v12, v2
	v_mov_b32_e32 v13, v2
	v_mov_b32_e32 v14, v2
	v_mov_b32_e32 v15, v2
	v_mov_b32_e32 v16, v2
	v_mov_b32_e32 v17, v2
	v_mov_b32_e32 v18, v2
	v_mov_b32_e32 v19, v2
	v_mov_b32_e32 v20, v2
	v_mov_b32_e32 v21, v2
	v_mov_b32_e32 v22, v2
	v_mov_b32_e32 v23, v2
	v_mov_b32_e32 v24, v2
	v_mov_b32_e32 v25, v2
	v_mov_b32_e32 v26, v2
	v_mov_b32_e32 v27, v2
	v_mov_b32_e32 v28, v2
	v_mov_b32_e32 v29, v2
	v_mov_b32_e32 v30, v2
	v_mov_b32_e32 v31, v2
	v_mov_b32_e32 v32, v2
	v_mov_b32_e32 v33, v2
	v_mov_b32_e32 v34, v2
	v_mov_b32_e32 v35, v2
	v_mov_b32_e32 v36, v2
	v_mov_b32_e32 v37, v2
	v_mov_b32_e32 v38, v2
	v_mov_b32_e32 v39, v2
	v_mov_b32_e32 v40, v2
	v_mov_b32_e32 v41, v2
	v_mov_b32_e32 v42, v2
	v_mov_b32_e32 v43, v2
	v_mov_b32_e32 v44, v2
	v_mov_b32_e32 v45, v2
	s_waitcnt vmcnt(0)
	v_mov_b32_e32 v46, v2
	v_mov_b32_e32 v47, v2
	v_mov_b32_e32 v48, v2
	v_mov_b32_e32 v49, v2
	v_mov_b32_e32 v50, v2
	v_mov_b32_e32 v51, v2
	v_mov_b32_e32 v52, v2
	v_mov_b32_e32 v53, v2
	v_mov_b32_e32 v54, v2
	v_mov_b32_e32 v55, v2
	v_mov_b32_e32 v56, v2
	v_mov_b32_e32 v57, v2
	v_mov_b32_e32 v58, v2
	v_mov_b32_e32 v59, v2
	v_mov_b32_e32 v60, v2
	v_mov_b32_e32 v61, v2
	v_mov_b32_e32 v62, v2
	v_mov_b32_e32 v63, v2
	v_mov_b32_e32 v64, v2
	v_mov_b32_e32 v65, v2
	.p2align	6

; #define LAS __attribute__((address_space(3)))
; __device__ __forceinline__ void witem_store(const Frame& F, const WItem& t, const f32x4 (&v)[16], LAS unsigned char* tile) {
;     const int i = F.lane & 31, hi = F.lane >> 5;
; #pragma unroll
;     for (int j = 0; j < 4; ++j) {
;         u32x4 o;
; #pragma unroll
;         for (int d = 0; d < 4; ++d) { int r = __builtin_amdgcn_cvt_pk_fp8_f32(v[4 * d][j] * t.scale, v[4 * d + 1][j] * t.scale, 0, false);
;             r = __builtin_amdgcn_cvt_pk_fp8_f32(v[4 * d + 2][j] * t.scale, v[4 * d + 3][j] * t.scale, r, true); o[d] = (unsigned)r; }
;         *(LAS u32x4*)(tile + (32 * j + i) * 272 + 32 * F.wave + 16 * hi) = o;
;     }
;     __syncthreads();
.LBB0_1347:
	v_mul_f32_e32 v149, v147, v38
	v_mul_f32_e32 v150, v147, v42
	v_mov_b32_e32 v148, v199
	v_cvt_pk_fp8_f32 v148, v149, v150
	v_mul_f32_e32 v149, v147, v46
	v_mul_f32_e32 v150, v147, v54
	v_mul_f32_e32 v151, v147, v66
	v_cvt_pk_fp8_f32 v148, v149, v150 op_sel:[0,0,1]
	v_mul_f32_e32 v150, v147, v58
	v_mov_b32_e32 v149, v199
	v_cvt_pk_fp8_f32 v149, v150, v151
	v_mul_f32_e32 v150, v147, v74
	v_mul_f32_e32 v151, v147, v78
	v_mul_f32_e32 v152, v147, v98
	v_cvt_pk_fp8_f32 v149, v150, v151 op_sel:[0,0,1]
	v_mul_f32_e32 v151, v147, v90
	v_mov_b32_e32 v150, v199
	v_cvt_pk_fp8_f32 v150, v151, v152
	v_mul_f32_e32 v151, v147, v106
	v_mul_f32_e32 v152, v147, v110
	v_mul_f32_e32 v153, v147, v118
	v_cvt_pk_fp8_f32 v150, v151, v152 op_sel:[0,0,1]
	v_mul_f32_e32 v152, v147, v114
	v_mov_b32_e32 v151, v199
	v_cvt_pk_fp8_f32 v151, v152, v153
	v_mul_f32_e32 v152, v147, v122
	v_mul_f32_e32 v153, v147, v126
	s_movk_i32 s7, 0xff80
	v_cvt_pk_fp8_f32 v151, v152, v153 op_sel:[0,0,1]
	v_mul_f32_e32 v152, v147, v99
	v_mul_f32_e32 v153, v147, v119
	s_ashr_i32 s37, s36, 31
	ds_write_b128 v141, v[148:151] offset:34816
	v_mul_f32_e32 v149, v147, v39
	v_mul_f32_e32 v150, v147, v43
	v_mov_b32_e32 v148, v199
	v_cvt_pk_fp8_f32 v148, v149, v150
	v_mul_f32_e32 v149, v147, v47
	v_mul_f32_e32 v150, v147, v55
	v_mul_f32_e32 v151, v147, v67
	v_cvt_pk_fp8_f32 v148, v149, v150 op_sel:[0,0,1]
	v_mul_f32_e32 v150, v147, v59
	v_mov_b32_e32 v149, v199
	v_cvt_pk_fp8_f32 v149, v150, v151
	v_mul_f32_e32 v150, v147, v75
	v_mul_f32_e32 v151, v147, v79
	v_cvt_pk_fp8_f32 v149, v150, v151 op_sel:[0,0,1]
	v_mul_f32_e32 v151, v147, v91
	v_mov_b32_e32 v150, v199
	v_cvt_pk_fp8_f32 v150, v151, v152
	v_mul_f32_e32 v151, v147, v107
	v_mul_f32_e32 v152, v147, v111
	v_cvt_pk_fp8_f32 v150, v151, v152 op_sel:[0,0,1]
	v_mul_f32_e32 v152, v147, v115
	v_mov_b32_e32 v151, v199
	v_cvt_pk_fp8_f32 v151, v152, v153
	v_mul_f32_e32 v152, v147, v123
	v_mul_f32_e32 v153, v147, v127
	v_cvt_pk_fp8_f32 v151, v152, v153 op_sel:[0,0,1]
	v_mul_f32_e32 v152, v147, v100
	v_mul_f32_e32 v153, v147, v120
	ds_write_b128 v141, v[148:151] offset:43520
	v_mul_f32_e32 v149, v147, v40
	v_mul_f32_e32 v150, v147, v44
	v_mov_b32_e32 v148, v199
	v_cvt_pk_fp8_f32 v148, v149, v150
	v_mul_f32_e32 v149, v147, v48
	v_mul_f32_e32 v150, v147, v56
	v_mul_f32_e32 v151, v147, v68
	v_cvt_pk_fp8_f32 v148, v149, v150 op_sel:[0,0,1]
	v_mul_f32_e32 v150, v147, v60
	v_mov_b32_e32 v149, v199
	v_cvt_pk_fp8_f32 v149, v150, v151
	v_mul_f32_e32 v150, v147, v76
	v_mul_f32_e32 v151, v147, v80
	v_cvt_pk_fp8_f32 v149, v150, v151 op_sel:[0,0,1]
	v_mul_f32_e32 v151, v147, v92
	v_mov_b32_e32 v150, v199
	v_cvt_pk_fp8_f32 v150, v151, v152
	v_mul_f32_e32 v151, v147, v108
	v_mul_f32_e32 v152, v147, v112
	v_cvt_pk_fp8_f32 v150, v151, v152 op_sel:[0,0,1]
	v_mul_f32_e32 v152, v147, v116
	v_mov_b32_e32 v151, v199
	v_cvt_pk_fp8_f32 v151, v152, v153
	v_mul_f32_e32 v152, v147, v124
	v_mul_f32_e32 v153, v147, v128
	v_cvt_pk_fp8_f32 v151, v152, v153 op_sel:[0,0,1]
	v_mul_f32_e32 v152, v147, v101
	v_mul_f32_e32 v153, v147, v121
	ds_write_b128 v141, v[148:151] offset:52224
	v_mul_f32_e32 v149, v147, v41
	v_mul_f32_e32 v150, v147, v45
	v_mov_b32_e32 v148, v199
	v_cvt_pk_fp8_f32 v148, v149, v150
	v_mul_f32_e32 v149, v147, v49
	v_mul_f32_e32 v150, v147, v57
	v_mul_f32_e32 v151, v147, v69
	v_cvt_pk_fp8_f32 v148, v149, v150 op_sel:[0,0,1]
	v_mul_f32_e32 v150, v147, v61
	v_mov_b32_e32 v149, v199
	v_cvt_pk_fp8_f32 v149, v150, v151
	v_mul_f32_e32 v150, v147, v77
	v_mul_f32_e32 v151, v147, v81
	v_cvt_pk_fp8_f32 v149, v150, v151 op_sel:[0,0,1]
	v_mul_f32_e32 v151, v147, v93
	v_mov_b32_e32 v150, v199
	v_cvt_pk_fp8_f32 v150, v151, v152
	v_mul_f32_e32 v151, v147, v109
	v_mul_f32_e32 v152, v147, v113
	v_cvt_pk_fp8_f32 v150, v151, v152 op_sel:[0,0,1]
	v_mul_f32_e32 v152, v147, v117
	v_mov_b32_e32 v151, v199
	v_cvt_pk_fp8_f32 v151, v152, v153
	v_mul_f32_e32 v152, v147, v125
	v_mul_f32_e32 v153, v147, v129
	v_cvt_pk_fp8_f32 v151, v152, v153 op_sel:[0,0,1]
	v_add_u32_e32 v152, s40, v131
	v_ashrrev_i32_e32 v153, 3, v152
	v_and_b32_e32 v154, 0x63, v152
	v_and_or_b32 v153, v153, s7, v154
	v_lshlrev_b32_e32 v154, 1, v152
	v_and_b32_e32 v154, 0x700, v154
	v_add_u32_e32 v153, v153, v154
	v_lshrrev_b32_e32 v154, 1, v152
	v_lshlrev_b32_e32 v152, 2, v152
	v_and_b32_e32 v154, 12, v154
	v_and_b32_e32 v152, 16, v152
	v_or3_b32 v152, v153, v154, v152
	ds_write_b128 v141, v[148:151] offset:60928
	s_waitcnt lgkmcnt(0)
	s_barrier
; #define LAS __attribute__((address_space(3)))
; __device__ __forceinline__ int map_row_rt(int map, int n) { return map == 0 ? n : (map == 1 ? map_row<1>(n) : (map == 3 ? map_row<3>(n) : map_row<2>(n))); }
; __device__ __forceinline__ void witem_store(const Frame& F, const WItem& t, const f32x4 (&v)[16], LAS unsigned char* tile) {
;     ...
;     const int c = F.tid & 15;
; #pragma unroll
;     for (int pass = 0; pass < 4; ++pass) { const int n = (F.tid >> 4) + 32 * pass, rho = (n & 3) * 32 + (n >> 2);
;         const u32x4 o = *(const LAS u32x4*)(tile + rho * 272 + 16 * c);
;         *(u32x4*)(t.WT + (size_t)map_row_rt(t.map, t.n0 + n) * D + t.k0 + 16 * c) = o; }
; }
; __device__ __forceinline__ void fp8_convert_range(const Frame& F, int l, int start, int stride, int limit) {
;     ...
;         if (ha) witem_load(ta, F.wave, F.lane, va);
;         witem_store(F, tb, vb, F.lds + 34816);
	ds_read_b128 v[148:151], v142 offset:34816
	v_ashrrev_i32_e32 v153, 31, v152
	v_lshlrev_b64 v[152:153], 10, v[152:153]
	v_lshl_add_u64 v[152:153], s[28:29], 0, v[152:153]
	v_lshl_add_u64 v[152:153], v[152:153], 0, s[36:37]
	v_lshl_add_u64 v[152:153], v[152:153], 0, v[132:133]
	s_waitcnt lgkmcnt(0)
	global_store_dwordx4 v[152:153], v[148:151], off
	v_add_u32_e32 v152, s40, v134
	v_ashrrev_i32_e32 v153, 3, v152
	v_and_b32_e32 v154, 0x63, v152
	v_and_or_b32 v153, v153, s7, v154
	v_lshlrev_b32_e32 v154, 1, v152
	v_and_b32_e32 v154, 0x700, v154
	v_add_u32_e32 v153, v153, v154
	v_lshrrev_b32_e32 v154, 1, v152
	v_lshlrev_b32_e32 v152, 2, v152
	v_and_b32_e32 v154, 12, v154
	v_and_b32_e32 v152, 16, v152
	v_or3_b32 v152, v153, v154, v152
	ds_read_b128 v[148:151], v143 offset:34816
	v_ashrrev_i32_e32 v153, 31, v152
	v_lshlrev_b64 v[152:153], 10, v[152:153]
	v_lshl_add_u64 v[152:153], s[28:29], 0, v[152:153]
	v_lshl_add_u64 v[152:153], v[152:153], 0, s[36:37]
	v_lshl_add_u64 v[152:153], v[152:153], 0, v[132:133]
	s_waitcnt lgkmcnt(0)
	global_store_dwordx4 v[152:153], v[148:151], off
	v_add_u32_e32 v152, s40, v135
	v_ashrrev_i32_e32 v153, 3, v152
	v_and_b32_e32 v154, 0x63, v152
	v_and_or_b32 v153, v153, s7, v154
	v_lshlrev_b32_e32 v154, 1, v152
	v_and_b32_e32 v154, 0x700, v154
	v_add_u32_e32 v153, v153, v154
	v_lshrrev_b32_e32 v154, 1, v152
	v_lshlrev_b32_e32 v152, 2, v152
	v_and_b32_e32 v154, 12, v154
	v_and_b32_e32 v152, 16, v152
	v_or3_b32 v152, v153, v154, v152
	ds_read_b128 v[148:151], v144 offset:34816
	v_ashrrev_i32_e32 v153, 31, v152
	v_lshlrev_b64 v[152:153], 10, v[152:153]
	v_lshl_add_u64 v[152:153], s[28:29], 0, v[152:153]
	v_lshl_add_u64 v[152:153], v[152:153], 0, s[36:37]
	v_lshl_add_u64 v[152:153], v[152:153], 0, v[132:133]
	s_waitcnt lgkmcnt(0)
	global_store_dwordx4 v[152:153], v[148:151], off
	v_add_u32_e32 v152, s40, v136
	v_ashrrev_i32_e32 v153, 3, v152
	v_and_b32_e32 v154, 0x63, v152
	v_and_or_b32 v153, v153, s7, v154
	v_lshlrev_b32_e32 v154, 1, v152
	v_and_b32_e32 v154, 0x700, v154
	v_add_u32_e32 v153, v153, v154
	v_lshrrev_b32_e32 v154, 1, v152
	v_lshlrev_b32_e32 v152, 2, v152
	v_and_b32_e32 v154, 12, v154
	v_and_b32_e32 v152, 16, v152
	v_or3_b32 v152, v153, v154, v152
	ds_read_b128 v[148:151], v145 offset:34816
	v_ashrrev_i32_e32 v153, 31, v152
	v_lshlrev_b64 v[152:153], 10, v[152:153]
	v_lshl_add_u64 v[152:153], s[28:29], 0, v[152:153]
	v_lshl_add_u64 v[152:153], v[152:153], 0, s[36:37]
	v_lshl_add_u64 v[152:153], v[152:153], 0, v[132:133]
	s_waitcnt lgkmcnt(0)
	global_store_dwordx4 v[152:153], v[148:151], off
	s_and_b64 vcc, exec, s[26:27]
	s_cbranch_vccnz .LBB0_1354
	.p2align	6

; #define LAS __attribute__((address_space(3)))
; __device__ __forceinline__ int map_row_rt(int map, int n) { return map == 0 ? n : (map == 1 ? map_row<1>(n) : (map == 3 ? map_row<3>(n) : map_row<2>(n))); }
; __device__ __forceinline__ void witem_store(const Frame& F, const WItem& t, const f32x4 (&v)[16], LAS unsigned char* tile) {
;     ...
;     for (int pass = 0; pass < 4; ++pass) { const int n = (F.tid >> 4) + 32 * pass, rho = (n & 3) * 32 + (n >> 2);
;         const u32x4 o = *(const LAS u32x4*)(tile + rho * 272 + 16 * c);
;         *(u32x4*)(t.WT + (size_t)map_row_rt(t.map, t.n0 + n) * D + t.k0 + 16 * c) = o; }
; }
.LBB0_1420:
	v_ashrrev_i32_e32 v139, 31, v138
	v_lshlrev_b64 v[138:139], 10, v[138:139]
	v_lshl_add_u64 v[138:139], s[42:43], 0, v[138:139]
	v_lshl_add_u64 v[138:139], v[138:139], 0, s[44:45]
	v_lshl_add_u64 v[138:139], v[138:139], 0, v[134:135]
	s_waitcnt lgkmcnt(0)
	global_store_dwordx4 v[138:139], v[130:133], off
	s_and_b64 vcc, exec, s[48:49]
	s_cbranch_vccnz .LBB0_1556
	.p2align	6

; #define LAS __attribute__((address_space(3)))
; __device__ __forceinline__ int map_row_rt(int map, int n) { return map == 0 ? n : (map == 1 ? map_row<1>(n) : (map == 3 ? map_row<3>(n) : map_row<2>(n))); }
; __device__ __forceinline__ void witem_store(const Frame& F, const WItem& t, const f32x4 (&v)[16], LAS unsigned char* tile) {
;     ...
;     for (int pass = 0; pass < 4; ++pass) { const int n = (F.tid >> 4) + 32 * pass, rho = (n & 3) * 32 + (n >> 2);
;         const u32x4 o = *(const LAS u32x4*)(tile + rho * 272 + 16 * c);
;         *(u32x4*)(t.WT + (size_t)map_row_rt(t.map, t.n0 + n) * D + t.k0 + 16 * c) = o; }
; }
.LBB0_1606:
	v_ashrrev_i32_e32 v139, 31, v138
	v_lshlrev_b64 v[138:139], 10, v[138:139]
	v_lshl_add_u64 v[138:139], s[44:45], 0, v[138:139]
	v_lshl_add_u64 v[138:139], v[138:139], 0, s[46:47]
	v_lshl_add_u64 v[138:139], v[138:139], 0, v[134:135]
	s_waitcnt lgkmcnt(0)
	global_store_dwordx4 v[138:139], v[130:133], off
	s_and_b64 vcc, exec, s[50:51]
	s_cbranch_vccnz .LBB0_1742
	.p2align	6

; #define LDS_BARRIER() do { asm volatile("s_waitcnt lgkmcnt(0)" ::: "memory"); __builtin_amdgcn_s_barrier(); asm volatile("" ::: "memory"); } while (0)
; template <int BR> __device__ __forceinline__ void nsa_softmax_pv(LAS unsigned char* L, int slot, const NsaBr& c, int j, f32x16 (&sa)[2], f32x16 (&oacc)[2], float& mrun, float& lrun) {
;     ...
;             for (int i = 0; i < 16; ++i) { const int key = 64 * j + 32 * kt + (i & 3) + 8 * (i >> 2) + 4 * h;
;                 int pb = (t - key) >> 31;
;                 if (BR == 2) pb |= (key - (t - 511)) >> 31;
;                 const float v = sa[kt][i] + __int_as_float(pb & (int)0xF149F2CA); sa[kt][i] = v; mblk = fmaxf(mblk, v); }
; template <int BR>
; __device__ __forceinline__ void nsa_branch(const Frame& F, int plane, int qt, int t, int r, int h, unsigned selmask, const bf16x8 (&qr)[4], float gate) {
;     ...
; #pragma unroll
;     for (int i = 0; i < 16; ++i) { oacc[0][i] = 0.f; oacc[1][i] = 0.f; }
;     float mrun = -1e20f, lrun = 0.f;
;     nsa_kv_load(c, c.jlo, kreg, vreg);
;     LDS_BARRIER();
;     nsa_kv_write(L, 0, c, kreg, vreg);
;     if (nblk > 1) nsa_kv_load(c, c.jlo + 1, kreg, vreg);
;     LDS_BARRIER();
;     if (nblk > 1) { nsa_kv_write(L, NL_SLOT, c, kreg, vreg); if (nblk > 2) nsa_kv_load(c, c.jlo + 2, kreg, vreg); }
;     nsa_s_tile<BR>(L, 0, c, qr, sa);
;     int s0 = 0, s1 = NL_SLOT, s2 = 2 * NL_SLOT;
; #pragma unroll 1
.LBB0_1762:
	v_add3_u32 v209, 0, v96, v97
	ds_read_b128 v[2:5], v209
	ds_read_b128 v[18:21], v209 offset:32
	s_movk_i32 s0, 0x88
	v_mul_lo_u32 v208, v130, s0
	s_and_b32 s0, s4, 15
	s_waitcnt lgkmcnt(1)
	v_mfma_f32_32x32x16_bf16 v[2:17], v[2:5], v[98:101], 0
	s_lshl_b32 s34, s0, 18
	s_mov_b32 s4, 0
	ds_read_b128 v[36:39], v209 offset:4640
	s_waitcnt lgkmcnt(1)
	v_mfma_f32_32x32x16_bf16 v[2:17], v[18:21], v[102:105], v[2:17]
	ds_read_b128 v[18:21], v209 offset:64
	s_waitcnt lgkmcnt(0)
	v_mfma_f32_32x32x16_bf16 v[2:17], v[18:21], v[106:109], v[2:17]
	ds_read_b128 v[18:21], v209 offset:96
	s_waitcnt lgkmcnt(0)
	v_mfma_f32_32x32x16_bf16 v[2:17], v[18:21], v[110:113], v[2:17]
	ds_read_b128 v[18:21], v209 offset:4608
	s_waitcnt lgkmcnt(0)
	v_mfma_f32_32x32x16_bf16 v[18:33], v[18:21], v[98:101], 0
	v_mfma_f32_32x32x16_bf16 v[18:33], v[36:39], v[102:105], v[18:33]
	ds_read_b128 v[36:39], v209 offset:4672
	s_waitcnt lgkmcnt(0)
	v_mfma_f32_32x32x16_bf16 v[18:33], v[36:39], v[106:109], v[18:33]
	ds_read_b128 v[36:39], v209 offset:4704
	s_waitcnt lgkmcnt(0)
	v_mfma_f32_32x32x16_bf16 v[18:33], v[36:39], v[110:113], v[18:33]
	s_setprio 0
	v_or_b32_e32 v214, s7, v204
	v_cmp_lt_i32_e32 vcc, v214, v128
	v_or_b32_e32 v216, 32, v214
	s_add_i32 s11, s8, -1
	v_cndmask_b32_e64 v165, v234, 0, vcc
	v_cmp_lt_i32_e32 vcc, v128, v214
	v_or_b32_e32 v125, 3, v214
	v_or_b32_e32 v122, 2, v214
	v_cndmask_b32_e32 v164, 0, v234, vcc
	v_or_b32_e32 v129, 9, v214
	v_or_b32_e32 v134, 8, v214
	v_or_b32_e32 v131, 11, v214
	v_or_b32_e32 v136, 10, v214
	v_or_b32_e32 v135, 17, v214
	v_or_b32_e32 v138, 16, v214
	v_or_b32_e32 v137, 19, v214
	v_or_b32_e32 v140, 18, v214
	v_or_b32_e32 v139, 25, v214
	v_or_b32_e32 v142, 24, v214
	v_or_b32_e32 v141, 27, v214
	v_or_b32_e32 v144, 26, v214
	v_cmp_lt_i32_e32 vcc, v216, v128
	v_or_b32_e32 v143, 35, v214
	v_or_b32_e32 v146, 34, v214
	v_or_b32_e32 v145, 41, v214
	v_or_b32_e32 v148, 40, v214
	v_or_b32_e32 v147, 43, v214
	v_or_b32_e32 v150, 42, v214
	v_or_b32_e32 v149, 49, v214
	v_or_b32_e32 v152, 48, v214
	v_or_b32_e32 v151, 51, v214
	v_or_b32_e32 v156, 50, v214
	v_or_b32_e32 v153, 57, v214
	v_or_b32_e32 v158, 56, v214
	v_or_b32_e32 v157, 59, v214
	v_or_b32_e32 v160, 58, v214
	s_add_u32 s14, s28, s34
	v_mul_u32_u24_e32 v210, 0x88, v83
	v_cmp_lt_i32_e64 s[0:1], v128, v125
	v_cmp_lt_i32_e64 s[40:41], v128, v122
	v_cmp_lt_i32_e64 s[42:43], v128, v129
	v_cmp_lt_i32_e64 s[44:45], v128, v134
	v_cmp_lt_i32_e64 s[46:47], v128, v131
	v_cmp_lt_i32_e64 s[48:49], v128, v136
	v_cmp_lt_i32_e64 s[50:51], v128, v135
	v_cmp_lt_i32_e64 s[52:53], v128, v138
	v_cmp_lt_i32_e64 s[54:55], v128, v137
	v_cmp_lt_i32_e64 s[56:57], v128, v140
	v_cmp_lt_i32_e64 s[58:59], v128, v139
	v_cmp_lt_i32_e64 s[60:61], v128, v142
	v_cmp_lt_i32_e64 s[62:63], v128, v141
	v_cmp_lt_i32_e64 s[64:65], v128, v144
	v_cndmask_b32_e64 v181, v234, 0, vcc
	v_cmp_lt_i32_e32 vcc, v128, v216
	v_cmp_lt_i32_e64 s[66:67], v128, v143
	v_cmp_lt_i32_e64 s[68:69], v128, v146
	v_cmp_lt_i32_e64 s[70:71], v128, v145
	v_cmp_lt_i32_e64 s[72:73], v128, v148
	v_cmp_lt_i32_e64 s[74:75], v128, v147
	v_cmp_lt_i32_e64 s[76:77], v128, v150
	v_cmp_lt_i32_e64 s[78:79], v128, v149
	v_cmp_lt_i32_e64 s[80:81], v128, v152
	v_cmp_lt_i32_e64 s[82:83], v128, v151
	v_cmp_lt_i32_e64 s[84:85], v128, v156
	v_cmp_lt_i32_e64 s[86:87], v128, v153
	v_cmp_lt_i32_e64 s[88:89], v128, v158
	v_cmp_lt_i32_e64 s[90:91], v128, v157
	v_cmp_lt_i32_e64 s[92:93], v128, v160
	s_addc_u32 s15, s29, 0
	v_lshl_add_u64 v[154:155], s[34:35], 0, v[162:163]
	v_mov_b32_e32 v133, 0
	v_mov_b32_e32 v1, v128
	v_cndmask_b32_e64 v167, 0, v234, s[0:1]
	v_cndmask_b32_e64 v166, 0, v234, s[40:41]
	v_cndmask_b32_e64 v169, 0, v234, s[42:43]
	v_cndmask_b32_e64 v168, 0, v234, s[44:45]
	v_cndmask_b32_e64 v171, 0, v234, s[46:47]
	v_cndmask_b32_e64 v170, 0, v234, s[48:49]
	v_cndmask_b32_e64 v173, 0, v234, s[50:51]
	v_cndmask_b32_e64 v172, 0, v234, s[52:53]
	v_cndmask_b32_e64 v175, 0, v234, s[54:55]
	v_cndmask_b32_e64 v174, 0, v234, s[56:57]
	v_cndmask_b32_e64 v177, 0, v234, s[58:59]
	v_cndmask_b32_e64 v176, 0, v234, s[60:61]
	v_cndmask_b32_e64 v179, 0, v234, s[62:63]
	v_cndmask_b32_e64 v178, 0, v234, s[64:65]
	v_cndmask_b32_e32 v180, 0, v234, vcc
	v_cndmask_b32_e64 v183, 0, v234, s[66:67]
	v_cndmask_b32_e64 v182, 0, v234, s[68:69]
	v_cndmask_b32_e64 v185, 0, v234, s[70:71]
	v_cndmask_b32_e64 v184, 0, v234, s[72:73]
	v_cndmask_b32_e64 v187, 0, v234, s[74:75]
	v_cndmask_b32_e64 v186, 0, v234, s[76:77]
	v_cndmask_b32_e64 v189, 0, v234, s[78:79]
	v_cndmask_b32_e64 v188, 0, v234, s[80:81]
	v_cndmask_b32_e64 v191, 0, v234, s[82:83]
	v_cndmask_b32_e64 v190, 0, v234, s[84:85]
	v_cndmask_b32_e64 v193, 0, v234, s[86:87]
	v_cndmask_b32_e64 v192, 0, v234, s[88:89]
	v_cndmask_b32_e64 v195, 0, v234, s[90:91]
	v_cndmask_b32_e64 v194, 0, v234, s[92:93]
	v_add3_u32 v211, 0, v206, v210
	v_lshl_add_u64 v[196:197], s[14:15], 0, v[34:35]
	v_lshl_add_u64 v[200:201], s[28:29], 0, v[154:155]
	v_mov_b32_e32 v218, 0xe0ad78ec
	s_mov_b32 s3, 0x8c00
	s_movk_i32 s30, 0x4600
	s_mov_b32 s31, 0
	v_mov_b32_e32 v34, 0
	v_mov_b32_e32 v35, v133
	v_mov_b32_e32 v36, v133
	v_mov_b32_e32 v37, v133
	v_mov_b32_e32 v38, v133
	v_mov_b32_e32 v39, v133
	v_mov_b32_e32 v40, v133
	v_mov_b32_e32 v41, v133
	v_mov_b32_e32 v42, v133
	v_mov_b32_e32 v43, v133
	v_mov_b32_e32 v44, v133
	v_mov_b32_e32 v45, v133
	v_mov_b32_e32 v46, v133
	v_mov_b32_e32 v47, v133
	v_mov_b32_e32 v48, v133
	v_mov_b32_e32 v49, v133
	v_mov_b32_e32 v50, v133
	v_mov_b32_e32 v51, v133
	v_mov_b32_e32 v52, v133
	v_mov_b32_e32 v53, v133
	v_mov_b32_e32 v54, v133
	v_mov_b32_e32 v55, v133
	v_mov_b32_e32 v56, v133
	v_mov_b32_e32 v57, v133
	v_mov_b32_e32 v58, v133
	v_mov_b32_e32 v59, v133
	v_mov_b32_e32 v60, v133
	v_mov_b32_e32 v61, v133
	v_mov_b32_e32 v62, v133
	v_mov_b32_e32 v63, v133
	v_mov_b32_e32 v64, v133
	v_mov_b32_e32 v65, v133
	.p2align	6

; #define LAS __attribute__((address_space(3)))
; #define LDS_BARRIER() do { asm volatile("s_waitcnt lgkmcnt(0)" ::: "memory"); __builtin_amdgcn_s_barrier(); asm volatile("" ::: "memory"); } while (0)
; template <int BR> __device__ __forceinline__ void nsa_softmax_pv(LAS unsigned char* L, int slot, const NsaBr& c, int j, f32x16 (&sa)[2], f32x16 (&oacc)[2], float& mrun, float& lrun) {
;     ...
;     const bool edge = (j == c.qt) || (BR == 2 && c.qt >= 8 && j == c.jlo);
;     if (edge) {
; #pragma unroll
;         for (int kt = 0; kt < 2; ++kt)
; #pragma unroll
;             for (int i = 0; i < 16; ++i) { const int key = 64 * j + 32 * kt + (i & 3) + 8 * (i >> 2) + 4 * h;
;                 int pb = (t - key) >> 31;
;                 if (BR == 2) pb |= (key - (t - 511)) >> 31;
;                 const float v = sa[kt][i] + __int_as_float(pb & (int)0xF149F2CA); sa[kt][i] = v; mblk = fmaxf(mblk, v); }
; template <int BR>
; __device__ __forceinline__ void nsa_branch(const Frame& F, int plane, int qt, int t, int r, int h, unsigned selmask, const bf16x8 (&qr)[4], float gate) {
;     LAS unsigned char* L = F.lds;
;     NsaBr c;
;     c.Kp = (const bf16*)(F.ws + (BR == 1 ? WS_NKS : WS_NKW)) + (size_t)plane * S * 64;
;     c.Vp = (const bf16*)(F.ws + (BR == 1 ? WS_NVST : WS_NVWT)) + (size_t)plane * 64 * S;
;     c.jlo = BR == 1 ? 0 : (qt > 8 ? qt - 8 : 0); c.srow = F.tid >> 3; c.spart = F.tid & 7; c.r = r; c.h = h; c.t = t; c.qt = qt; c.selmask = selmask; c.hiw = F.wave < 4;
;     const int nblk = qt - c.jlo + 1;
;     u32x4 kreg, vreg;
;     f32x16 oacc[2], sa[2], sb[2];
; #pragma unroll
;     for (int i = 0; i < 16; ++i) { oacc[0][i] = 0.f; oacc[1][i] = 0.f; }
;     float mrun = -1e20f, lrun = 0.f;
;     nsa_kv_load(c, c.jlo, kreg, vreg);
;     LDS_BARRIER();
;     nsa_kv_write(L, 0, c, kreg, vreg);
;     if (nblk > 1) nsa_kv_load(c, c.jlo + 1, kreg, vreg);
;     LDS_BARRIER();
;     if (nblk > 1) { nsa_kv_write(L, NL_SLOT, c, kreg, vreg); if (nblk > 2) nsa_kv_load(c, c.jlo + 2, kreg, vreg); }
;     nsa_s_tile<BR>(L, 0, c, qr, sa);
;     int s0 = 0, s1 = NL_SLOT, s2 = 2 * NL_SLOT;
.LBB0_1814:
	ds_read_b128 v[4:7], v209
	ds_read_b128 v[8:11], v209 offset:32
	v_cmp_lt_i32_e64 s[94:95], v128, v214
	v_cmp_lt_i32_e64 s[96:97], v128, v216
	s_mov_b32 s4, 0
	s_waitcnt lgkmcnt(1)
	v_mfma_f32_32x32x16_bf16 v[34:49], v[4:7], v[98:101], 0
	ds_read_b128 v[4:7], v209 offset:64
	s_waitcnt lgkmcnt(1)
	v_mfma_f32_32x32x16_bf16 v[34:49], v[8:11], v[102:105], v[34:49]
	s_waitcnt lgkmcnt(0)
	v_mfma_f32_32x32x16_bf16 v[34:49], v[4:7], v[106:109], v[34:49]
	ds_read_b128 v[4:7], v209 offset:96
	s_waitcnt lgkmcnt(0)
	v_mfma_f32_32x32x16_bf16 v[34:49], v[4:7], v[110:113], v[34:49]
	ds_read_b128 v[4:7], v209 offset:4608
	s_waitcnt lgkmcnt(0)
	v_mfma_f32_32x32x16_bf16 v[50:65], v[4:7], v[98:101], 0
	ds_read_b128 v[4:7], v209 offset:4640
	s_waitcnt lgkmcnt(0)
	v_mfma_f32_32x32x16_bf16 v[50:65], v[4:7], v[102:105], v[50:65]
	ds_read_b128 v[4:7], v209 offset:4672
	s_waitcnt lgkmcnt(0)
	v_mfma_f32_32x32x16_bf16 v[50:65], v[4:7], v[106:109], v[50:65]
	ds_read_b128 v[4:7], v209 offset:4704
	s_waitcnt lgkmcnt(0)
	v_mfma_f32_32x32x16_bf16 v[50:65], v[4:7], v[110:113], v[50:65]
	s_setprio 0
	s_add_i32 s5, s9, -3
	s_add_i32 s27, s9, -4
	s_add_i32 s11, s9, -2
	v_add_u32_e32 v162, 0xfffffe01, v128
	v_mov_b32_e32 v133, v199
	s_cmp_gt_u32 s8, 7
	v_cmp_lt_i32_e32 vcc, v214, v162
	v_lshl_add_u64 v[132:133], v[2:3], 0, v[132:133]
	s_cselect_b64 s[14:15], -1, 0
	s_or_b64 vcc, s[94:95], vcc
	v_or_b32_e32 v2, 1, v214
	v_cndmask_b32_e32 v163, 0, v234, vcc
	v_cmp_le_i32_e32 vcc, v128, v214
	v_cmp_lt_i32_e64 s[94:95], v2, v162
	s_or_b64 vcc, vcc, s[94:95]
	v_cndmask_b32_e32 v164, 0, v234, vcc
	v_cmp_lt_i32_e32 vcc, v122, v162
	s_or_b64 vcc, s[40:41], vcc
	v_or_b32_e32 v2, 33, v214
	v_cndmask_b32_e32 v165, 0, v234, vcc
	v_cmp_lt_i32_e32 vcc, v125, v162
	s_or_b64 vcc, s[0:1], vcc
	v_cmp_lt_i32_e64 s[0:1], v2, v162
	v_cndmask_b32_e32 v125, 0, v234, vcc
	v_cmp_lt_i32_e32 vcc, v134, v162
	s_or_b64 vcc, s[44:45], vcc
	s_lshl_b32 s8, s9, 6
	v_cndmask_b32_e32 v166, 0, v234, vcc
	v_cmp_lt_i32_e32 vcc, v129, v162
	s_or_b64 vcc, s[42:43], vcc
	v_add_u32_e32 v2, s7, v130
	v_cndmask_b32_e32 v129, 0, v234, vcc
	v_cmp_lt_i32_e32 vcc, v136, v162
	s_or_b64 vcc, s[48:49], vcc
	v_subrev_u32_e32 v4, s8, v2
	v_cndmask_b32_e32 v167, 0, v234, vcc
	v_cmp_lt_i32_e32 vcc, v131, v162
	s_or_b64 vcc, s[46:47], vcc
	s_sub_i32 s48, s8, 64
	v_cndmask_b32_e32 v168, 0, v234, vcc
	v_cmp_lt_i32_e32 vcc, v138, v162
	s_or_b64 vcc, s[52:53], vcc
	v_add_u32_e32 v2, 0x100, v4
	v_cndmask_b32_e32 v169, 0, v234, vcc
	v_cmp_lt_i32_e32 vcc, v135, v162
	s_or_b64 vcc, s[50:51], vcc
	v_ashrrev_i32_e32 v3, 31, v2
	v_cndmask_b32_e32 v170, 0, v234, vcc
	v_cmp_lt_i32_e32 vcc, v140, v162
	s_or_b64 vcc, s[56:57], vcc
	v_lshlrev_b64 v[2:3], 7, v[2:3]
	v_cndmask_b32_e32 v140, 0, v234, vcc
	v_cmp_lt_i32_e32 vcc, v137, v162
	s_or_b64 vcc, s[54:55], vcc
	v_mov_b32_e32 v123, v162
	v_cndmask_b32_e32 v171, 0, v234, vcc
	v_cmp_lt_i32_e32 vcc, v142, v162
	s_or_b64 vcc, s[60:61], vcc
	v_mov_b32_e32 v174, 0xe0ad78ec
	v_cndmask_b32_e32 v142, 0, v234, vcc
	v_cmp_lt_i32_e32 vcc, v139, v162
	s_or_b64 vcc, s[58:59], vcc
	s_mov_b32 s49, 0x8c00
	v_cndmask_b32_e32 v139, 0, v234, vcc
	v_cmp_lt_i32_e32 vcc, v144, v162
	s_or_b64 vcc, s[64:65], vcc
	s_mov_b64 s[94:95], 0x11000000
	v_cndmask_b32_e32 v144, 0, v234, vcc
	v_cmp_lt_i32_e32 vcc, v141, v162
	s_or_b64 vcc, s[62:63], vcc
	s_nop 0
	v_cndmask_b32_e32 v141, 0, v234, vcc
	v_cmp_lt_i32_e32 vcc, v216, v162
	s_or_b64 vcc, s[96:97], vcc
	v_readlane_b32 s96, v249, 56
	v_cndmask_b32_e32 v172, 0, v234, vcc
	v_cmp_le_i32_e32 vcc, v128, v216
	s_or_b64 vcc, vcc, s[0:1]
	v_readlane_b32 s97, v249, 57
	v_cndmask_b32_e32 v173, 0, v234, vcc
	v_cmp_lt_i32_e32 vcc, v146, v162
	s_or_b64 vcc, s[68:69], vcc
	s_nop 0
	v_cndmask_b32_e32 v146, 0, v234, vcc
	v_cmp_lt_i32_e32 vcc, v143, v162
	s_or_b64 vcc, s[66:67], vcc
	s_nop 0
	v_cndmask_b32_e32 v143, 0, v234, vcc
	v_cmp_lt_i32_e32 vcc, v148, v162
	s_or_b64 vcc, s[72:73], vcc
	s_nop 0
	v_cndmask_b32_e32 v148, 0, v234, vcc
	v_cmp_lt_i32_e32 vcc, v145, v162
	s_or_b64 vcc, s[70:71], vcc
	s_nop 0
	v_cndmask_b32_e32 v145, 0, v234, vcc
	v_cmp_lt_i32_e32 vcc, v150, v162
	s_or_b64 vcc, s[76:77], vcc
	s_nop 0
	v_cndmask_b32_e32 v150, 0, v234, vcc
	v_cmp_lt_i32_e32 vcc, v147, v162
	s_or_b64 vcc, s[74:75], vcc
	s_nop 0
	v_cndmask_b32_e32 v147, 0, v234, vcc
	v_cmp_lt_i32_e32 vcc, v152, v162
	s_or_b64 vcc, s[80:81], vcc
	v_readlane_b32 s80, v249, 42
	v_cndmask_b32_e32 v152, 0, v234, vcc
	v_cmp_lt_i32_e32 vcc, v149, v162
	s_or_b64 vcc, s[78:79], vcc
	v_readlane_b32 s78, v248, 23
	v_cndmask_b32_e32 v149, 0, v234, vcc
	v_cmp_lt_i32_e32 vcc, v156, v162
	s_or_b64 vcc, s[84:85], vcc
	v_readlane_b32 s81, v249, 43
	v_cndmask_b32_e32 v156, 0, v234, vcc
	v_cmp_lt_i32_e32 vcc, v151, v162
	s_or_b64 vcc, s[82:83], vcc
	v_readlane_b32 s79, v248, 24
	v_cndmask_b32_e32 v151, 0, v234, vcc
	v_cmp_lt_i32_e32 vcc, v158, v162
	s_or_b64 vcc, s[88:89], vcc
	s_brev_b32 s82, -2
	v_cndmask_b32_e32 v158, 0, v234, vcc
	v_cmp_lt_i32_e32 vcc, v153, v162
	s_or_b64 vcc, s[86:87], vcc
	s_mov_b32 s83, 0xbfb8aa3b
	v_cndmask_b32_e32 v153, 0, v234, vcc
	v_cmp_lt_i32_e32 vcc, v160, v162
	s_or_b64 vcc, s[92:93], vcc
	s_mov_b32 s92, 0x42ce8ed0
	v_cndmask_b32_e32 v160, 0, v234, vcc
	v_cmp_lt_i32_e32 vcc, v157, v162
	s_or_b64 vcc, s[90:91], vcc
	s_add_u32 s0, s3, s34
	s_addc_u32 s1, s10, 0
	v_lshl_add_u64 v[130:131], s[0:1], 0, v[2:3]
	v_add_u32_e32 v2, 0xc0, v4
	v_ashrrev_i32_e32 v3, 31, v2
	v_lshlrev_b64 v[2:3], 7, v[2:3]
	v_lshl_add_u64 v[134:135], s[0:1], 0, v[2:3]
	s_lshl_b32 s0, s26, 1
	s_add_u32 s0, s28, s0
	s_addc_u32 s1, s29, 0
	v_lshl_add_u64 v[2:3], s[0:1], 0, v[154:155]
	s_mov_b64 s[0:1], 0x6ec00180
	v_lshl_add_u64 v[136:137], v[2:3], 0, s[0:1]
	v_add_u32_e32 v2, s7, v204
	v_mov_b32_e32 v155, 0
	v_cndmask_b32_e32 v157, 0, v234, vcc
	v_subrev_u32_e32 v154, s8, v2
	s_movk_i32 s7, 0x4600
	s_mov_b32 s0, 0
	s_mov_b32 s3, 0
	v_mov_b32_e32 v2, 0
	v_mov_b32_e32 v3, v155
	v_mov_b32_e32 v4, v155
	v_mov_b32_e32 v5, v155
	v_mov_b32_e32 v6, v155
	v_mov_b32_e32 v7, v155
	v_mov_b32_e32 v8, v155
	v_mov_b32_e32 v9, v155
	v_mov_b32_e32 v10, v155
	v_mov_b32_e32 v11, v155
	v_mov_b32_e32 v12, v155
	v_mov_b32_e32 v13, v155
	v_mov_b32_e32 v14, v155
	v_mov_b32_e32 v15, v155
	v_mov_b32_e32 v16, v155
	v_mov_b32_e32 v17, v155
	v_mov_b32_e32 v18, v155
	v_mov_b32_e32 v19, v155
	v_mov_b32_e32 v20, v155
	v_mov_b32_e32 v21, v155
	v_mov_b32_e32 v22, v155
	v_mov_b32_e32 v23, v155
	v_mov_b32_e32 v24, v155
	v_mov_b32_e32 v25, v155
	v_mov_b32_e32 v26, v155
	v_mov_b32_e32 v27, v155
	v_mov_b32_e32 v28, v155
	v_mov_b32_e32 v29, v155
	v_mov_b32_e32 v30, v155
	v_mov_b32_e32 v31, v155
	v_mov_b32_e32 v32, v155
	v_mov_b32_e32 v33, v155
	s_mov_b32 s93, 0xc2b17218
	.p2align	6

; template <bool FP8, class Epi, class Sched, class ARow, class BBase>
; __device__ __forceinline__ void gemm_phase(LAS unsigned char* lds, const void* Abase, const ARow& AR, const BBase& BB, const Sched& S, const Epi& E, int tid) {
;     ...
;             *(LAS u32x4*)(lds + NA_OFF + tid * 16) = (u32x4){nA[0][0], nA[0][1], nA[1][0], nA[1][1]};
;         }
;         if constexpr (Epi::PREFETCH) E.prefetch(lds + (ui & 1) * SB_SIZE, cur, tid);
;         for (int t = 0; t < nt; t += 2) {
;             const bool last = (t == nt - 2);
;             const unsigned k1 = (unsigned)((t + 1) * kstep), kb2 = last ? 0u : (unsigned)((t + 2) * kstep);
;             const char* b2 = last ? nB : cB + (size_t)(t + 2) * kstep; const char* b3 = b2 + kstep;
;             PG8_LDB(B0, 0, 0); PG8_LDB(B1, 0, 1); PG8_SCHED; PG8_LDA(At, 0, 0); PG8_STAGEA(PG8_SA(1, 1), cA, 1, k1);
;             if (last) { const u32x4 q = *(const LAS u32x4*)(lds + NA_OFF + tid * 16); cA[0][0] = q.x; cA[0][1] = q.y; cA[1][0] = q.z; cA[1][1] = q.w; }
;             PG8_WAIT_V(8); PG8_WAIT_L(0); PG8_BAR; PG8_MMA(0, 0, At, B0); PG8_MMA(0, 1, At, B1); PG8_BAR; PG8_SCHED;
;             PG8_LDA(At, 0, 1); PG8_STAGEB(PG8_SB(0, 0), b2); PG8_STAGEB(PG8_SB(0, 1), b2 + hstep); PG8_STAGEA(PG8_SA(0, 0), cA, 0, kb2);
;             PG8_WAIT_V(8); PG8_WAIT_L(0); PG8_BAR; PG8_MMA(1, 0, At, B0); PG8_MMA(1, 1, At, B1); PG8_BAR; PG8_SCHED;
;             PG8_LDB(B0, 1, 0); PG8_LDB(B1, 1, 1); PG8_SCHED; PG8_LDA(At, 1, 0); PG8_STAGEA(PG8_SA(0, 1), cA, 1, kb2);
;             PG8_WAIT_V(8); PG8_WAIT_L(0); PG8_BAR; PG8_MMA(0, 0, At, B0); PG8_MMA(0, 1, At, B1); PG8_BAR; PG8_SCHED;
;             PG8_LDA(At, 1, 1); PG8_STAGEB(PG8_SB(1, 0), b3); PG8_STAGEB(PG8_SB(1, 1), b3 + hstep); PG8_STAGEA(PG8_SA(1, 0), cA, 0, kb2 + (unsigned)kstep);
;             PG8_WAIT_V(8); PG8_WAIT_L(0); PG8_BAR; PG8_MMA(1, 0, At, B0); PG8_MMA(1, 1, At, B1); PG8_BAR; PG8_SCHED;
;         }
;         if (wr == 0) PG8_BAR;
;         { int efr = fr, efq = fq; asm volatile("" : "+v"(efr), "+v"(efq));
;           if constexpr (Epi::PREFETCH) E(acc, cur, wr, wc, efr, efq, lds + (ui & 1) * SB_SIZE); else E(acc, cur, wr, wc, efr, efq); }
;         if (!has_next) break;
; #pragma unroll
;         for (int a = 0; a < 2; ++a)
; #pragma unroll
;             for (int b = 0; b < 2; ++b)
; #pragma unroll
;                 for (int m = 0; m < 4; ++m)
; #pragma unroll
.LBB0_2066:
	v_add_u32_e32 v10, 0, v1
	v_add_u32_e32 v206, 0x20400, v10
	ds_write_b128 v206, v[6:9]
	s_add_u32 s4, s26, 0x100
	v_mov_b32_e32 v6, 0
	s_addc_u32 s5, s27, 0
	s_mov_b32 s45, -2
	s_mov_b64 s[26:27], 0
	v_mov_b32_e32 v7, v6
	v_mov_b32_e32 v8, v6
	v_mov_b32_e32 v9, v6
	v_mov_b32_e32 v10, v6
	v_mov_b32_e32 v11, v6
	v_mov_b32_e32 v12, v6
	v_mov_b32_e32 v13, v6
	v_mov_b32_e32 v18, v6
	v_mov_b32_e32 v19, v6
	v_mov_b32_e32 v20, v6
	v_mov_b32_e32 v21, v6
	v_mov_b32_e32 v26, v6
	v_mov_b32_e32 v27, v6
	v_mov_b32_e32 v28, v6
	v_mov_b32_e32 v29, v6
	v_mov_b32_e32 v34, v6
	v_mov_b32_e32 v35, v6
	v_mov_b32_e32 v36, v6
	v_mov_b32_e32 v37, v6
	v_mov_b32_e32 v42, v6
	v_mov_b32_e32 v43, v6
	v_mov_b32_e32 v44, v6
	v_mov_b32_e32 v45, v6
	v_mov_b32_e32 v50, v6
	v_mov_b32_e32 v51, v6
	v_mov_b32_e32 v52, v6
	v_mov_b32_e32 v53, v6
	v_mov_b32_e32 v58, v6
	v_mov_b32_e32 v59, v6
	v_mov_b32_e32 v60, v6
	v_mov_b32_e32 v61, v6
	v_mov_b32_e32 v14, v6
	v_mov_b32_e32 v15, v6
	v_mov_b32_e32 v16, v6
	v_mov_b32_e32 v17, v6
	v_mov_b32_e32 v22, v6
	v_mov_b32_e32 v23, v6
	v_mov_b32_e32 v24, v6
	v_mov_b32_e32 v25, v6
	v_mov_b32_e32 v30, v6
	v_mov_b32_e32 v31, v6
	v_mov_b32_e32 v32, v6
	v_mov_b32_e32 v33, v6
	v_mov_b32_e32 v38, v6
	v_mov_b32_e32 v39, v6
	v_mov_b32_e32 v40, v6
	v_mov_b32_e32 v41, v6
	v_mov_b32_e32 v46, v6
	v_mov_b32_e32 v47, v6
	v_mov_b32_e32 v48, v6
	v_mov_b32_e32 v49, v6
	v_mov_b32_e32 v54, v6
	v_mov_b32_e32 v55, v6
	v_mov_b32_e32 v56, v6
	v_mov_b32_e32 v57, v6
	v_mov_b32_e32 v62, v6
	v_mov_b32_e32 v63, v6
	v_mov_b32_e32 v64, v6
	v_mov_b32_e32 v65, v6
	v_mov_b32_e32 v66, v6
	v_mov_b32_e32 v67, v6
	v_mov_b32_e32 v68, v6
	v_mov_b32_e32 v69, v6
	v_mov_b32_e32 v70, v6
	v_mov_b32_e32 v71, v6
	v_mov_b32_e32 v72, v6
	v_mov_b32_e32 v73, v6
	v_mov_b32_e32 v74, v6
	v_mov_b32_e32 v75, v6
	v_mov_b32_e32 v76, v6
	v_mov_b32_e32 v77, v6
	v_mov_b32_e32 v82, v6
	v_mov_b32_e32 v83, v6
	v_mov_b32_e32 v84, v6
	v_mov_b32_e32 v85, v6
	v_mov_b32_e32 v90, v6
	v_mov_b32_e32 v91, v6
	v_mov_b32_e32 v92, v6
	v_mov_b32_e32 v93, v6
	v_mov_b32_e32 v98, v6
	v_mov_b32_e32 v99, v6
	v_mov_b32_e32 v100, v6
	v_mov_b32_e32 v101, v6
	v_mov_b32_e32 v106, v6
	v_mov_b32_e32 v107, v6
	v_mov_b32_e32 v108, v6
	v_mov_b32_e32 v109, v6
	v_mov_b32_e32 v114, v6
	v_mov_b32_e32 v115, v6
	v_mov_b32_e32 v116, v6
	v_mov_b32_e32 v117, v6
	v_mov_b32_e32 v122, v6
	v_mov_b32_e32 v123, v6
	v_mov_b32_e32 v124, v6
	v_mov_b32_e32 v125, v6
	v_mov_b32_e32 v78, v6
	v_mov_b32_e32 v79, v6
	v_mov_b32_e32 v80, v6
	v_mov_b32_e32 v81, v6
	v_mov_b32_e32 v86, v6
	v_mov_b32_e32 v87, v6
	v_mov_b32_e32 v88, v6
	v_mov_b32_e32 v89, v6
	v_mov_b32_e32 v94, v6
	v_mov_b32_e32 v95, v6
	v_mov_b32_e32 v96, v6
	v_mov_b32_e32 v97, v6
	v_mov_b32_e32 v102, v6
	v_mov_b32_e32 v103, v6
	v_mov_b32_e32 v104, v6
	v_mov_b32_e32 v105, v6
	v_mov_b32_e32 v110, v6
	v_mov_b32_e32 v111, v6
	v_mov_b32_e32 v112, v6
	v_mov_b32_e32 v113, v6
	v_mov_b32_e32 v118, v6
	v_mov_b32_e32 v119, v6
	v_mov_b32_e32 v120, v6
	v_mov_b32_e32 v121, v6
	v_mov_b32_e32 v126, v6
	v_mov_b32_e32 v127, v6
	v_mov_b32_e32 v128, v6
	v_mov_b32_e32 v129, v6
	v_mov_b32_e32 v130, v6
	v_mov_b32_e32 v131, v6
	v_mov_b32_e32 v132, v6
	v_mov_b32_e32 v133, v6
	.p2align	6

; __device__ __forceinline__ void phase_row1(const Frame& F, int l) {
;     ...
;         f32x4 g1[4], vlg[4], vlb[4], sc1[4], sh[4];
;         { const float* modp = MOD + ((size_t)l * 8 + ((chunk * 64) >> 11)) * 6144;
;           load_row(modp + 2048, lane, g1); load_row(F.in[12] + (l * 2 + 0) * D, lane, vlg); load_row(F.in[13] + (l * 2 + 0) * D, lane, vlb); load_row(modp + 3 * 1024, lane, sh); load_row(modp + 4 * 1024, lane, sc1);
; #pragma unroll
;           for (int j = 0; j < 4; ++j) { g1[j] = g1[j] + 1.f; sc1[j] = sc1[j] + 1.f; } }
;         f32x4 cx[4], nx[4]; u32x2 cy[4], ny[4];
;         { const int row = chunk * 64 + w * 8; if (l == 0) load_row(F.in[0] + (size_t)row * D, lane, cx); else load_row_bf16(XB + (size_t)row * D, lane, cx);
; #pragma unroll
;           for (int j = 0; j < 4; ++j) cy[j] = *(const u32x2*)((const bf16*)(F.ws + WS_MIX) + (size_t)row * D + 256 * j + 4 * lane); }
.LBB0_2140:
	v_lshl_add_u64 v[146:147], v[118:119], 0, s[26:27]
	global_load_dwordx2 v[152:153], v[146:147], off
	global_load_dwordx2 v[150:151], v[146:147], off offset:512
	global_load_dwordx2 v[148:149], v[146:147], off offset:1024
	s_nop 0
	global_load_dwordx2 v[146:147], v[146:147], off offset:1536
	v_and_b32_e32 v158, 64, v225
	v_add_u32_e32 v163, 64, v158
	v_xor_b32_e32 v135, 32, v225
	v_cmp_lt_i32_e32 vcc, v135, v163
	v_xor_b32_e32 v159, 16, v225
	v_xor_b32_e32 v160, 8, v225
	v_cndmask_b32_e32 v135, v225, v135, vcc
	v_cmp_lt_i32_e32 vcc, v159, v163
	v_xor_b32_e32 v161, 4, v225
	v_xor_b32_e32 v162, 2, v225
	v_cndmask_b32_e32 v159, v225, v159, vcc
	v_cmp_lt_i32_e32 vcc, v160, v163
	v_xor_b32_e32 v164, 1, v225
	s_waitcnt vmcnt(21)
	v_pk_add_f32 v[96:97], v[96:97], 1.0 op_sel_hi:[1,0]
	v_cndmask_b32_e32 v160, v225, v160, vcc
	v_cmp_lt_i32_e32 vcc, v161, v163
	v_pk_add_f32 v[94:95], v[94:95], 1.0 op_sel_hi:[1,0]
	s_waitcnt vmcnt(5)
	v_pk_add_f32 v[112:113], v[112:113], 1.0 op_sel_hi:[1,0]
	v_cndmask_b32_e32 v161, v225, v161, vcc
	v_cmp_lt_i32_e32 vcc, v162, v163
	v_pk_add_f32 v[110:111], v[110:111], 1.0 op_sel_hi:[1,0]
	v_pk_add_f32 v[92:93], v[92:93], 1.0 op_sel_hi:[1,0]
	v_cndmask_b32_e32 v162, v225, v162, vcc
	v_cmp_lt_i32_e32 vcc, v164, v163
	v_pk_add_f32 v[90:91], v[90:91], 1.0 op_sel_hi:[1,0]
	v_pk_add_f32 v[108:109], v[108:109], 1.0 op_sel_hi:[1,0]
	v_cndmask_b32_e32 v163, v225, v164, vcc
	v_pk_add_f32 v[106:107], v[106:107], 1.0 op_sel_hi:[1,0]
	v_pk_add_f32 v[88:89], v[88:89], 1.0 op_sel_hi:[1,0]
	v_pk_add_f32 v[86:87], v[86:87], 1.0 op_sel_hi:[1,0]
	v_pk_add_f32 v[104:105], v[104:105], 1.0 op_sel_hi:[1,0]
	v_pk_add_f32 v[102:103], v[102:103], 1.0 op_sel_hi:[1,0]
	v_pk_add_f32 v[84:85], v[84:85], 1.0 op_sel_hi:[1,0]
	v_pk_add_f32 v[82:83], v[82:83], 1.0 op_sel_hi:[1,0]
	s_waitcnt vmcnt(0)
	v_pk_add_f32 v[100:101], v[100:101], 1.0 op_sel_hi:[1,0]
	v_pk_add_f32 v[98:99], v[98:99], 1.0 op_sel_hi:[1,0]
	s_mov_b32 s6, 0
	v_lshlrev_b32_e32 v135, 2, v135
	v_lshlrev_b32_e32 v159, 2, v159
	v_lshlrev_b32_e32 v160, 2, v160
	v_lshlrev_b32_e32 v161, 2, v161
	v_lshlrev_b32_e32 v162, 2, v162
	v_lshlrev_b32_e32 v163, 2, v163
	s_add_i32 s26, s11, s6
	s_cmp_eq_u32 s6, 7
	s_cbranch_scc1 .LBB0_2147
	s_branch .LBB0_2142
	.p2align	6

; #define LAS __attribute__((address_space(3)))
; template <bool FP8, class Epi, class Sched, class ARow, class BBase>
; __device__ __forceinline__ void gemm_phase(LAS unsigned char* lds, const void* Abase, const ARow& AR, const BBase& BB, const Sched& S, const Epi& E, int tid) {
;     ...
;         for (int a = 0; a < 2; ++a)
; #pragma unroll
;             for (int b = 0; b < 2; ++b)
; #pragma unroll
;                 for (int m = 0; m < 4; ++m)
; #pragma unroll
;                     for (int n = 0; n < 2; ++n) acc[a][b][m][n] = (f32x4){0.f, 0.f, 0.f, 0.f};
;     __device__ __forceinline__ void prefetch(LAS unsigned char* lds, const pg8::Unit& u, int tid) const {
;         const int wv = __builtin_amdgcn_readfirstlane(tid >> 6), i = tid & 255;
;         const float* g = tid < 256 ? lhs + (size_t)u.e * T + u.lrow0 + (i < u.nvalid ? i : u.nvalid - 1)
;                                    : bias_l + (size_t)u.e * 2048 + 128 * u.pn + (i < 128 ? i : 1024 + (i - 128));
;         __builtin_amdgcn_global_load_lds((const unsigned*)g, (LAS unsigned*)(lds + SB_OFF + wv * 256), 4, 0, 0);
.LBB0_2235:
	s_or_b64 exec, exec, s[4:5]
	s_bitcmp1_b32 s30, 0
	s_cselect_b32 s3, 0xc00, 0
	s_add_i32 s3, s3, 0
	s_lshl_b32 s5, s31, 2
	s_add_i32 s4, s3, 0x22400
	s_and_b32 s5, s5, 0xffffff00
	s_add_i32 m0, s4, s5
	s_add_u32 s5, s26, 0x100
	global_load_lds_dword v[2:3], off
	v_mov_b32_e32 v70, 0
	s_addc_u32 s30, s27, 0
	s_mov_b32 s31, -2
	s_mov_b64 s[26:27], 0
	v_mov_b32_e32 v71, v70
	v_mov_b32_e32 v72, v70
	v_mov_b32_e32 v73, v70
	v_mov_b32_e32 v78, v70
	v_mov_b32_e32 v79, v70
	v_mov_b32_e32 v80, v70
	v_mov_b32_e32 v81, v70
	v_mov_b32_e32 v86, v70
	v_mov_b32_e32 v87, v70
	v_mov_b32_e32 v88, v70
	v_mov_b32_e32 v89, v70
	v_mov_b32_e32 v94, v70
	v_mov_b32_e32 v95, v70
	v_mov_b32_e32 v96, v70
	v_mov_b32_e32 v97, v70
	v_mov_b32_e32 v102, v70
	v_mov_b32_e32 v103, v70
	v_mov_b32_e32 v104, v70
	v_mov_b32_e32 v105, v70
	v_mov_b32_e32 v110, v70
	v_mov_b32_e32 v111, v70
	v_mov_b32_e32 v112, v70
	v_mov_b32_e32 v113, v70
	v_mov_b32_e32 v114, v70
	v_mov_b32_e32 v115, v70
	v_mov_b32_e32 v116, v70
	v_mov_b32_e32 v117, v70
	v_mov_b32_e32 v122, v70
	v_mov_b32_e32 v123, v70
	v_mov_b32_e32 v124, v70
	v_mov_b32_e32 v125, v70
	v_mov_b32_e32 v74, v70
	v_mov_b32_e32 v75, v70
	v_mov_b32_e32 v76, v70
	v_mov_b32_e32 v77, v70
	v_mov_b32_e32 v82, v70
	v_mov_b32_e32 v83, v70
	v_mov_b32_e32 v84, v70
	v_mov_b32_e32 v85, v70
	v_mov_b32_e32 v90, v70
	v_mov_b32_e32 v91, v70
	v_mov_b32_e32 v92, v70
	v_mov_b32_e32 v93, v70
	v_mov_b32_e32 v98, v70
	v_mov_b32_e32 v99, v70
	v_mov_b32_e32 v100, v70
	v_mov_b32_e32 v101, v70
	v_mov_b32_e32 v106, v70
	v_mov_b32_e32 v107, v70
	v_mov_b32_e32 v108, v70
	v_mov_b32_e32 v109, v70
	v_mov_b32_e32 v118, v70
	v_mov_b32_e32 v119, v70
	v_mov_b32_e32 v120, v70
	v_mov_b32_e32 v121, v70
	v_mov_b32_e32 v126, v70
	v_mov_b32_e32 v127, v70
	v_mov_b32_e32 v128, v70
	v_mov_b32_e32 v129, v70
	v_mov_b32_e32 v130, v70
	v_mov_b32_e32 v131, v70
	v_mov_b32_e32 v132, v70
	v_mov_b32_e32 v133, v70
	v_mov_b32_e32 v134, v70
	v_mov_b32_e32 v135, v70
	v_mov_b32_e32 v136, v70
	v_mov_b32_e32 v137, v70
	v_mov_b32_e32 v142, v70
	v_mov_b32_e32 v143, v70
	v_mov_b32_e32 v144, v70
	v_mov_b32_e32 v145, v70
	v_mov_b32_e32 v150, v70
	v_mov_b32_e32 v151, v70
	v_mov_b32_e32 v152, v70
	v_mov_b32_e32 v153, v70
	v_mov_b32_e32 v158, v70
	v_mov_b32_e32 v159, v70
	v_mov_b32_e32 v160, v70
	v_mov_b32_e32 v161, v70
	v_mov_b32_e32 v166, v70
	v_mov_b32_e32 v167, v70
	v_mov_b32_e32 v168, v70
	v_mov_b32_e32 v169, v70
	v_mov_b32_e32 v174, v70
	v_mov_b32_e32 v175, v70
	v_mov_b32_e32 v176, v70
	v_mov_b32_e32 v177, v70
	v_mov_b32_e32 v178, v70
	v_mov_b32_e32 v179, v70
	v_mov_b32_e32 v180, v70
	v_mov_b32_e32 v181, v70
	v_mov_b32_e32 v190, v70
	v_mov_b32_e32 v191, v70
	v_mov_b32_e32 v192, v70
	v_mov_b32_e32 v193, v70
	v_mov_b32_e32 v138, v70
	v_mov_b32_e32 v139, v70
	v_mov_b32_e32 v140, v70
	v_mov_b32_e32 v141, v70
	v_mov_b32_e32 v146, v70
	v_mov_b32_e32 v147, v70
	v_mov_b32_e32 v148, v70
	v_mov_b32_e32 v149, v70
	v_mov_b32_e32 v154, v70
	v_mov_b32_e32 v155, v70
	v_mov_b32_e32 v156, v70
	v_mov_b32_e32 v157, v70
	v_mov_b32_e32 v162, v70
	v_mov_b32_e32 v163, v70
	v_mov_b32_e32 v164, v70
	v_mov_b32_e32 v165, v70
	v_mov_b32_e32 v170, v70
	v_mov_b32_e32 v171, v70
	v_mov_b32_e32 v172, v70
	v_mov_b32_e32 v173, v70
	v_mov_b32_e32 v182, v70
	v_mov_b32_e32 v183, v70
	v_mov_b32_e32 v184, v70
	v_mov_b32_e32 v185, v70
	v_mov_b32_e32 v186, v70
	v_mov_b32_e32 v187, v70
	v_mov_b32_e32 v188, v70
	v_mov_b32_e32 v189, v70
	v_mov_b32_e32 v194, v70
	v_mov_b32_e32 v195, v70
	v_mov_b32_e32 v196, v70
	v_mov_b32_e32 v197, v70
	.p2align	6

; #define LAS __attribute__((address_space(3)))
; template <bool FP8, class Epi, class Sched, class ARow, class BBase>
; __device__ __forceinline__ void gemm_phase(LAS unsigned char* lds, const void* Abase, const ARow& AR, const BBase& BB, const Sched& S, const Epi& E, int tid) {
;     ...
;         for (int a = 0; a < 2; ++a)
; #pragma unroll
;             for (int b = 0; b < 2; ++b)
; #pragma unroll
;                 for (int m = 0; m < 4; ++m)
; #pragma unroll
;                     for (int n = 0; n < 2; ++n) acc[a][b][m][n] = (f32x4){0.f, 0.f, 0.f, 0.f};
;     __device__ __forceinline__ void prefetch(LAS unsigned char* lds, const pg8::Unit& u, int tid) const {
;         const int wv = __builtin_amdgcn_readfirstlane(tid >> 6), i = tid & 255;
;         const size_t ri = (size_t)u.e * T + u.lrow0 + (i < u.nvalid ? i : u.nvalid - 1);
;         if (wv < 4) {
;             __builtin_amdgcn_global_load_lds((const unsigned*)(list + ri), (LAS unsigned*)(lds + SB_OFF + wv * 256), 4, 0, 0);
;             __builtin_amdgcn_global_load_lds((const unsigned*)(lgw + ri), (LAS unsigned*)(lds + SB_OFF + 1024 + wv * 256), 4, 0, 0);
;         } else
;             __builtin_amdgcn_global_load_lds((const unsigned*)(bias_l + (size_t)u.e * D + 256 * u.pn + i), (LAS unsigned*)(lds + SB_OFF + 2048 + (wv - 4) * 256), 4, 0, 0);
;     }
.LBB0_2340:
	s_add_i32 s5, s4, 0x22800
	s_add_i32 m0, s5, s51
	s_add_u32 s33, s56, 0x100
	global_load_lds_dword v[2:3], off
	v_mov_b32_e32 v70, 0
	s_addc_u32 s49, s57, 0
	s_mov_b32 s51, -2
	s_mov_b64 s[26:27], 0
	v_mov_b32_e32 v71, v70
	v_mov_b32_e32 v72, v70
	v_mov_b32_e32 v73, v70
	v_mov_b32_e32 v74, v70
	v_mov_b32_e32 v75, v70
	v_mov_b32_e32 v76, v70
	v_mov_b32_e32 v77, v70
	v_mov_b32_e32 v86, v70
	v_mov_b32_e32 v87, v70
	v_mov_b32_e32 v88, v70
	v_mov_b32_e32 v89, v70
	v_mov_b32_e32 v90, v70
	v_mov_b32_e32 v91, v70
	v_mov_b32_e32 v92, v70
	v_mov_b32_e32 v93, v70
	v_mov_b32_e32 v102, v70
	v_mov_b32_e32 v103, v70
	v_mov_b32_e32 v104, v70
	v_mov_b32_e32 v105, v70
	v_mov_b32_e32 v106, v70
	v_mov_b32_e32 v107, v70
	v_mov_b32_e32 v108, v70
	v_mov_b32_e32 v109, v70
	v_mov_b32_e32 v118, v70
	v_mov_b32_e32 v119, v70
	v_mov_b32_e32 v120, v70
	v_mov_b32_e32 v121, v70
	v_mov_b32_e32 v122, v70
	v_mov_b32_e32 v123, v70
	v_mov_b32_e32 v124, v70
	v_mov_b32_e32 v125, v70
	v_mov_b32_e32 v78, v70
	v_mov_b32_e32 v79, v70
	v_mov_b32_e32 v80, v70
	v_mov_b32_e32 v81, v70
	v_mov_b32_e32 v82, v70
	v_mov_b32_e32 v83, v70
	v_mov_b32_e32 v84, v70
	v_mov_b32_e32 v85, v70
	v_mov_b32_e32 v94, v70
	v_mov_b32_e32 v95, v70
	v_mov_b32_e32 v96, v70
	v_mov_b32_e32 v97, v70
	v_mov_b32_e32 v98, v70
	v_mov_b32_e32 v99, v70
	v_mov_b32_e32 v100, v70
	v_mov_b32_e32 v101, v70
	v_mov_b32_e32 v110, v70
	v_mov_b32_e32 v111, v70
	v_mov_b32_e32 v112, v70
	v_mov_b32_e32 v113, v70
	v_mov_b32_e32 v114, v70
	v_mov_b32_e32 v115, v70
	v_mov_b32_e32 v116, v70
	v_mov_b32_e32 v117, v70
	v_mov_b32_e32 v126, v70
	v_mov_b32_e32 v127, v70
	v_mov_b32_e32 v128, v70
	v_mov_b32_e32 v129, v70
	v_mov_b32_e32 v130, v70
	v_mov_b32_e32 v131, v70
	v_mov_b32_e32 v132, v70
	v_mov_b32_e32 v133, v70
	v_mov_b32_e32 v134, v70
	v_mov_b32_e32 v135, v70
	v_mov_b32_e32 v136, v70
	v_mov_b32_e32 v137, v70
	v_mov_b32_e32 v138, v70
	v_mov_b32_e32 v139, v70
	v_mov_b32_e32 v140, v70
	v_mov_b32_e32 v141, v70
	v_mov_b32_e32 v150, v70
	v_mov_b32_e32 v151, v70
	v_mov_b32_e32 v152, v70
	v_mov_b32_e32 v153, v70
	v_mov_b32_e32 v154, v70
	v_mov_b32_e32 v155, v70
	v_mov_b32_e32 v156, v70
	v_mov_b32_e32 v157, v70
	v_mov_b32_e32 v166, v70
	v_mov_b32_e32 v167, v70
	v_mov_b32_e32 v168, v70
	v_mov_b32_e32 v169, v70
	v_mov_b32_e32 v170, v70
	v_mov_b32_e32 v171, v70
	v_mov_b32_e32 v172, v70
	v_mov_b32_e32 v173, v70
	v_mov_b32_e32 v182, v70
	v_mov_b32_e32 v183, v70
	v_mov_b32_e32 v184, v70
	v_mov_b32_e32 v185, v70
	v_mov_b32_e32 v186, v70
	v_mov_b32_e32 v187, v70
	v_mov_b32_e32 v188, v70
	v_mov_b32_e32 v189, v70
	v_mov_b32_e32 v142, v70
	v_mov_b32_e32 v143, v70
	v_mov_b32_e32 v144, v70
	v_mov_b32_e32 v145, v70
	v_mov_b32_e32 v146, v70
	v_mov_b32_e32 v147, v70
	v_mov_b32_e32 v148, v70
	v_mov_b32_e32 v149, v70
	v_mov_b32_e32 v158, v70
	v_mov_b32_e32 v159, v70
	v_mov_b32_e32 v160, v70
	v_mov_b32_e32 v161, v70
	v_mov_b32_e32 v162, v70
	v_mov_b32_e32 v163, v70
	v_mov_b32_e32 v164, v70
	v_mov_b32_e32 v165, v70
	v_mov_b32_e32 v174, v70
	v_mov_b32_e32 v175, v70
	v_mov_b32_e32 v176, v70
	v_mov_b32_e32 v177, v70
	v_mov_b32_e32 v178, v70
	v_mov_b32_e32 v179, v70
	v_mov_b32_e32 v180, v70
	v_mov_b32_e32 v181, v70
	v_mov_b32_e32 v190, v70
	v_mov_b32_e32 v191, v70
	v_mov_b32_e32 v192, v70
	v_mov_b32_e32 v193, v70
	v_mov_b32_e32 v194, v70
	v_mov_b32_e32 v195, v70
	v_mov_b32_e32 v196, v70
	v_mov_b32_e32 v197, v70
	.p2align	6

; __device__ __forceinline__ void phase_row2(const Frame& F, int l) {
;     ...
;         f32x4 g1[4], lg[4], lb[4], sc1[4], sh[4];
;         load_row8(modp + 5 * 1024, lane, g1); load_row8(F.in[12] + (l * 2 + 1) * D, lane, lg); load_row8(F.in[13] + (l * 2 + 1) * D, lane, lb);
; #pragma unroll
;         for (int j = 0; j < 4; ++j) g1[j] = g1[j] + 1.f;
;         if (l + 1 < DEPTH) { const float* modn = MOD + ((size_t)(l + 1) * 8 + b) * 6144; load_row8(modn, lane, sh); load_row8(modn + 1024, lane, sc1);
; #pragma unroll
;             for (int j = 0; j < 4; ++j) sc1[j] = sc1[j] + 1.f; }
;         else {
; #pragma unroll
;             for (int j = 0; j < 4; ++j) { sh[j] = (f32x4){0.f, 0.f, 0.f, 0.f}; sc1[j] = sh[j]; } }
;         u32x4 cxb[2], nxb[2], cy[4][2], ny[4][2];
;         { const bf16* yk = (const bf16*)(F.ws + WS_YK) + (size_t)row0 * 4 * D + 8 * lane;
; #pragma unroll
;           for (int j2 = 0; j2 < 2; ++j2) { cxb[j2] = *(const u32x4*)(XB + (size_t)row0 * D + 512 * j2 + 8 * lane);
; #pragma unroll
;               for (int k = 0; k < 4; ++k) cy[k][j2] = *(const u32x4*)(yk + k * D + 512 * j2); } }
.LBB0_2425:
	s_ashr_i32 s37, s36, 31
	s_lshl_b64 s[0:1], s[36:37], 13
	v_lshl_add_u64 v[50:51], v[112:113], 0, s[0:1]
	s_lshl_b64 s[0:1], s[36:37], 11
	v_lshl_add_u64 v[52:53], v[108:109], 0, s[0:1]
	v_add_co_u32_e32 v136, vcc, 0x1000, v50
	s_waitcnt vmcnt(11)
	v_pk_add_f32 v[148:149], v[100:101], 1.0 op_sel_hi:[1,0]
	v_addc_co_u32_e32 v137, vcc, 0, v51, vcc
	global_load_dwordx4 v[86:89], v[52:53], off
	global_load_dwordx4 v[66:69], v[52:53], off offset:1024
	global_load_dwordx4 v[82:85], v[50:51], off
	global_load_dwordx4 v[62:65], v[50:51], off offset:1024
	global_load_dwordx4 v[78:81], v[50:51], off offset:2048
	global_load_dwordx4 v[58:61], v[50:51], off offset:3072
	global_load_dwordx4 v[74:77], v[136:137], off
	global_load_dwordx4 v[54:57], v[136:137], off offset:1024
	global_load_dwordx4 v[70:73], v[136:137], off offset:2048
	s_nop 0
	global_load_dwordx4 v[50:53], v[136:137], off offset:3072
	v_pk_add_f32 v[150:151], v[98:99], 1.0 op_sel_hi:[1,0]
	s_waitcnt vmcnt(19)
	v_pk_add_f32 v[144:145], v[104:105], 1.0 op_sel_hi:[1,0]
	v_pk_add_f32 v[146:147], v[102:103], 1.0 op_sel_hi:[1,0]
	s_waitcnt vmcnt(18)
	v_pk_add_f32 v[140:141], v[96:97], 1.0 op_sel_hi:[1,0]
	v_pk_add_f32 v[142:143], v[94:95], 1.0 op_sel_hi:[1,0]
	v_pk_add_f32 v[136:137], v[92:93], 1.0 op_sel_hi:[1,0]
	v_pk_add_f32 v[138:139], v[90:91], 1.0 op_sel_hi:[1,0]
	s_mov_b32 s10, 0
	s_branch .LBB0_2427
	.p2align	6
